# v42 + FoX loop trims (max canonicalisation, zero-init packed adds)
# baseline (speedup 1.0000x reference)
; #define MFMA(a, b, c) __builtin_amdgcn_mfma_f32_32x32x16_bf16((a), (b), (c), 0, 0, 0)
; DI unsigned pack2(float a, float b) { f32x2 v = {a, b}; return __builtin_bit_cast(unsigned, __builtin_convertvector(v, bf16v2)); }
; template <int DK, int MODE> ...
;     ...
;         float mx = s0[0];
; #pragma unroll
;         for (int e = 1; e < 16; ++e) mx = fmaxf(mx, s0[e]);
; #pragma unroll
;         for (int e = 0; e < 16; ++e) mx = fmaxf(mx, s1[e]);
;         mx = fmaxf(mx, __shfl_xor(mx, 32));
;         if (__any(mx > m + 8.f)) {
;           const float mnew = fmaxf(m, mx);
;           const float alpha = __builtin_amdgcn_exp2f(m - mnew);
;           m = mnew; lsum *= alpha;
; #pragma unroll
;           for (int e = 0; e < 16; ++e) { o0[e] *= alpha; o1[e] *= alpha; }
;         }
;         float ps0 = 0.f, ps1 = 0.f, ps2 = 0.f, ps3 = 0.f;
; #pragma unroll
;         for (int e = 0; e < 16; e += 4) {
;           s0[e] = __builtin_amdgcn_exp2f(s0[e] - m); s0[e + 1] = __builtin_amdgcn_exp2f(s0[e + 1] - m); s0[e + 2] = __builtin_amdgcn_exp2f(s0[e + 2] - m); s0[e + 3] = __builtin_amdgcn_exp2f(s0[e + 3] - m);
;           ps0 += s0[e]; ps1 += s0[e + 1]; ps2 += s0[e + 2]; ps3 += s0[e + 3];
;         }
; #pragma unroll
;         for (int e = 0; e < 16; e += 4) {
;           s1[e] = __builtin_amdgcn_exp2f(s1[e] - m); s1[e + 1] = __builtin_amdgcn_exp2f(s1[e + 1] - m); s1[e + 2] = __builtin_amdgcn_exp2f(s1[e + 2] - m); s1[e + 3] = __builtin_amdgcn_exp2f(s1[e + 3] - m);
;           ps0 += s1[e]; ps1 += s1[e + 1]; ps2 += s1[e + 2]; ps3 += s1[e + 3];
;         }
;         lsum += (ps0 + ps1) + (ps2 + ps3);
;     ...
; #pragma unroll
;       for (int j = 0; j < 2; ++j) {
;         u32x4 a, b;
;         a.x = pack2(s0[8 * j], s0[8 * j + 1]); a.y = pack2(s0[8 * j + 2], s0[8 * j + 3]); a.z = pack2(s0[8 * j + 4], s0[8 * j + 5]); a.w = pack2(s0[8 * j + 6], s0[8 * j + 7]);
;         b.x = pack2(s1[8 * j], s1[8 * j + 1]); b.y = pack2(s1[8 * j + 2], s1[8 * j + 3]); b.z = pack2(s1[8 * j + 4], s1[8 * j + 5]); b.w = pack2(s1[8 * j + 6], s1[8 * j + 7]);
;         pf[j] = __builtin_bit_cast(bf16x8, a); pf[2 + j] = __builtin_bit_cast(bf16x8, b);
;       }
;       __builtin_amdgcn_s_setprio(1);
; #pragma unroll
;       for (int j = 0; j < 4; ++j) { o0 = MFMA(vf0[j], pf[j], o0); o1 = MFMA(vf1[j], pf[j], o1); }
;       __builtin_amdgcn_s_setprio(0);
.LBB0_565:
	s_nop 5
	v_max_f32_e32 v164, v50, v51
	v_max3_f32 v164, v164, v52, v53
	v_max3_f32 v164, v164, v54, v55
	v_max3_f32 v164, v164, v56, v57
	v_max3_f32 v164, v164, v58, v59
	v_max3_f32 v164, v164, v60, v61
	v_max3_f32 v164, v164, v62, v63
	v_max3_f32 v164, v164, v64, v65
	v_max3_f32 v164, v164, v34, v35
	v_max3_f32 v164, v164, v36, v37
	v_max3_f32 v164, v164, v38, v39
	v_max3_f32 v164, v164, v40, v41
	v_max3_f32 v164, v164, v42, v43
	v_max3_f32 v164, v164, v44, v45
	v_max3_f32 v164, v164, v46, v47
	v_max3_f32 v164, v164, v48, v49
	ds_bpermute_b32 v165, v151, v164
	s_waitcnt lgkmcnt(0)
	v_max_f32_e32 v164, v164, v165
	v_add_f32_e32 v165, 0x41000000, v163
	v_cmp_gt_f32_e32 vcc, v164, v165
	s_cbranch_vccz .LBB0_567
	v_max_f32_e32 v164, v164, v164
	v_max_f32_e32 v165, v163, v163
	v_max_f32_e32 v165, v165, v164
	v_sub_f32_e32 v163, v163, v165
	v_exp_f32_e32 v164, v163
	v_mov_b32_e32 v163, v165
	v_pk_mul_f32 v[32:33], v[32:33], v[164:165] op_sel_hi:[1,0]
	v_pk_mul_f32 v[30:31], v[30:31], v[164:165] op_sel_hi:[1,0]
	v_pk_mul_f32 v[28:29], v[28:29], v[164:165] op_sel_hi:[1,0]
	v_pk_mul_f32 v[26:27], v[26:27], v[164:165] op_sel_hi:[1,0]
	v_pk_mul_f32 v[24:25], v[24:25], v[164:165] op_sel_hi:[1,0]
	v_pk_mul_f32 v[22:23], v[22:23], v[164:165] op_sel_hi:[1,0]
	v_pk_mul_f32 v[20:21], v[20:21], v[164:165] op_sel_hi:[1,0]
	v_pk_mul_f32 v[18:19], v[18:19], v[164:165] op_sel_hi:[1,0]
	v_pk_mul_f32 v[16:17], v[16:17], v[164:165] op_sel_hi:[1,0]
	v_pk_mul_f32 v[14:15], v[14:15], v[164:165] op_sel_hi:[1,0]
	v_pk_mul_f32 v[12:13], v[12:13], v[164:165] op_sel_hi:[1,0]
	v_pk_mul_f32 v[10:11], v[10:11], v[164:165] op_sel_hi:[1,0]
	v_pk_mul_f32 v[8:9], v[8:9], v[164:165] op_sel_hi:[1,0]
	v_pk_mul_f32 v[6:7], v[6:7], v[164:165] op_sel_hi:[1,0]
	v_pk_mul_f32 v[4:5], v[4:5], v[164:165] op_sel_hi:[1,0]
	v_pk_mul_f32 v[2:3], v[2:3], v[164:165] op_sel_hi:[1,0]
	v_mul_f32_e32 v135, v135, v164
.LBB0_567:
	v_sub_f32_e32 v51, v51, v163
	v_exp_f32_e32 v164, v51
	v_sub_f32_e32 v51, v52, v163
	v_sub_f32_e32 v52, v53, v163
	v_sub_f32_e32 v53, v55, v163
	v_sub_f32_e32 v55, v57, v163
	v_sub_f32_e32 v57, v59, v163
	v_sub_f32_e32 v59, v61, v163
	v_sub_f32_e32 v61, v63, v163
	v_sub_f32_e32 v34, v34, v163
	v_exp_f32_e32 v165, v52
	v_sub_f32_e32 v52, v54, v163
	v_exp_f32_e32 v54, v53
	v_sub_f32_e32 v53, v56, v163
	v_sub_f32_e32 v56, v58, v163
	v_exp_f32_e32 v58, v57
	v_sub_f32_e32 v57, v60, v163
	v_sub_f32_e32 v60, v62, v163
	v_exp_f32_e32 v62, v61
	v_sub_f32_e32 v61, v64, v163
	v_exp_f32_e32 v64, v34
	v_sub_f32_e32 v34, v35, v163
	v_exp_f32_e32 v166, v34
	v_sub_f32_e32 v34, v36, v163
	v_sub_f32_e32 v63, v65, v163
	v_exp_f32_e32 v65, v34
	v_sub_f32_e32 v34, v37, v163
	v_exp_f32_e32 v167, v34
	v_sub_f32_e32 v34, v38, v163
	v_exp_f32_e32 v168, v34
	v_sub_f32_e32 v34, v39, v163
	v_exp_f32_e32 v170, v34
	v_sub_f32_e32 v34, v40, v163
	v_exp_f32_e32 v169, v34
	v_sub_f32_e32 v34, v41, v163
	v_exp_f32_e32 v171, v34
	v_sub_f32_e32 v34, v42, v163
	v_exp_f32_e32 v172, v34
	v_sub_f32_e32 v34, v43, v163
	v_exp_f32_e32 v174, v34
	v_sub_f32_e32 v34, v44, v163
	v_sub_f32_e32 v50, v50, v163
	v_exp_f32_e32 v173, v34
	v_sub_f32_e32 v34, v45, v163
	v_exp_f32_e32 v50, v50
	v_exp_f32_e32 v51, v51
	v_exp_f32_e32 v175, v34
	v_sub_f32_e32 v34, v46, v163
	v_exp_f32_e32 v52, v52
	v_exp_f32_e32 v53, v53
	v_exp_f32_e32 v55, v55
	v_exp_f32_e32 v176, v34
	v_sub_f32_e32 v34, v47, v163
	v_exp_f32_e32 v56, v56
	v_exp_f32_e32 v57, v57
	v_exp_f32_e32 v59, v59
	v_exp_f32_e32 v178, v34
	v_sub_f32_e32 v34, v48, v163
	v_exp_f32_e32 v60, v60
	v_exp_f32_e32 v61, v61
	v_exp_f32_e32 v63, v63
	v_exp_f32_e32 v177, v34
	v_sub_f32_e32 v34, v49, v163
	v_exp_f32_e32 v179, v34
	v_pk_add_f32 v[34:35], v[52:53], v[50:51]
	v_pk_add_f32 v[36:37], v[54:55], v[164:165]
	v_pk_add_f32 v[34:35], v[56:57], v[34:35]
	v_pk_add_f32 v[36:37], v[58:59], v[36:37]
	v_pk_add_f32 v[180:181], v[60:61], v[34:35]
	v_pk_add_f32 v[182:183], v[62:63], v[36:37]
	v_cvt_pk_bf16_f32 v34, v50, v164
	v_cvt_pk_bf16_f32 v35, v51, v165
	v_cvt_pk_bf16_f32 v36, v52, v54
	v_cvt_pk_bf16_f32 v37, v53, v55
	v_pk_add_f32 v[50:51], v[64:65], v[180:181]
	v_pk_add_f32 v[52:53], v[166:167], v[182:183]
	v_pk_add_f32 v[50:51], v[168:169], v[50:51]
	v_pk_add_f32 v[52:53], v[170:171], v[52:53]
	v_pk_add_f32 v[50:51], v[172:173], v[50:51]
	v_pk_add_f32 v[52:53], v[174:175], v[52:53]
	v_pk_add_f32 v[50:51], v[176:177], v[50:51]
	v_pk_add_f32 v[52:53], v[178:179], v[52:53]
	v_cvt_pk_bf16_f32 v38, v64, v166
	v_pk_add_f32 v[50:51], v[50:51], v[52:53]
	v_cvt_pk_bf16_f32 v39, v65, v167
	v_cvt_pk_bf16_f32 v40, v168, v170
	v_cvt_pk_bf16_f32 v41, v169, v171
	v_cvt_pk_bf16_f32 v42, v56, v58
	v_cvt_pk_bf16_f32 v43, v57, v59
	v_cvt_pk_bf16_f32 v44, v60, v62
	v_cvt_pk_bf16_f32 v45, v61, v63
	v_cvt_pk_bf16_f32 v46, v172, v174
	v_cvt_pk_bf16_f32 v47, v173, v175
	v_cvt_pk_bf16_f32 v48, v176, v178
	v_cvt_pk_bf16_f32 v49, v177, v179
	v_add_f32_e32 v50, v50, v51
	s_setprio 1
	v_mfma_f32_32x32x16_bf16 v[18:33], v[122:125], v[34:37], v[18:33]
	v_add_f32_e32 v135, v135, v50
	v_mfma_f32_32x32x16_bf16 v[2:17], v[126:129], v[34:37], v[2:17]
	v_mfma_f32_32x32x16_bf16 v[18:33], v[114:117], v[42:45], v[18:33]
	v_mfma_f32_32x32x16_bf16 v[2:17], v[118:121], v[42:45], v[2:17]
	v_mfma_f32_32x32x16_bf16 v[18:33], v[106:109], v[38:41], v[18:33]
	v_mfma_f32_32x32x16_bf16 v[2:17], v[110:113], v[38:41], v[2:17]
	v_mfma_f32_32x32x16_bf16 v[18:33], v[102:105], v[46:49], v[18:33]
	v_mfma_f32_32x32x16_bf16 v[2:17], v[98:101], v[46:49], v[2:17]
	s_setprio 0
